# v16 + pass2 item prologue: hipcc's serialized first preparation replaced by the transposed 8-byte preparation block
# baseline (speedup 1.0000x reference)
.LBB0_1326:
	v_readfirstlane_b32 s19, v17
	s_ashr_i32 s20, s18, 6
	s_ashr_i32 s26, s19, 6
	s_ashr_i32 s21, s20, 31
	s_lshl_b32 s19, s18, 8
	s_lshl_b64 s[20:21], s[20:21], 12
	s_and_b32 s19, s19, 0xf00
	s_or_b32 s22, s20, s19
	s_mov_b32 s23, s21
	s_waitcnt vmcnt(4)
	v_lshl_add_u64 v[8:9], s[22:23], 0, v[74:75]
	v_mov_b64_e32 v[10:11], s[52:53]
	s_movk_i32 s19, 0x1600
	v_mad_u64_u32 v[10:11], s[22:23], v8, s19, v[10:11]
	v_mad_i32_i24 v11, v9, s19, v11
	s_lshl_b32 s19, s18, 4
	s_and_b32 s54, s19, 0x300
	v_lshl_add_u64 v[8:9], v[10:11], 0, s[54:55]
	v_mov_b32_e32 v87, v16
	v_lshl_add_u64 v[26:27], v[8:9], 0, v[86:87]
	global_load_dwordx4 v[8:11], v[26:27], off offset:1536
	global_load_dwordx4 v[12:15], v[26:27], off offset:2560
	global_load_dwordx4 v[18:21], v[26:27], off offset:3584
	s_waitcnt vmcnt(4)
	v_add_co_u32_e32 v22, vcc, s68, v26
	s_ashr_i32 s19, s18, 31
	s_nop 0
	v_addc_co_u32_e32 v23, vcc, 0, v27, vcc
	global_load_dwordx4 v[22:25], v[22:23], off offset:512
	s_lshl_b64 s[22:23], s[18:19], 15
	s_add_u32 s22, s62, s22
	s_addc_u32 s23, s63, s23
	v_lshl_or_b32 v28, s26, 11, v92
	s_lshl_b32 s27, s26, 4
	v_ashrrev_i32_e32 v29, 31, v28
	v_or_b32_e32 v42, s27, v95
	v_lshl_add_u64 v[28:29], v[28:29], 1, s[22:23]
	v_ashrrev_i32_e32 v43, 31, v42
	global_load_dwordx2 v[38:39], v[28:29], off
	global_load_dwordx2 v[34:35], v[28:29], off offset:512
	global_load_dwordx2 v[36:37], v[28:29], off offset:1024
	global_load_dwordx2 v[40:41], v[28:29], off offset:1536
	global_load_dwordx2 v[44:45], v[28:29], off offset:2048
	global_load_dwordx2 v[48:49], v[28:29], off offset:2560
	global_load_dwordx2 v[52:53], v[28:29], off offset:3072
	global_load_dwordx2 v[56:57], v[28:29], off offset:3584
	v_lshl_add_u64 v[28:29], v[42:43], 2, s[70:71]
	global_load_dword v87, v[28:29], off
	v_add_u32_e32 v28, v76, v80
	s_mov_b32 s19, 0x2d000
	v_lshlrev_b32_e32 v122, 1, v42
	v_and_or_b32 v43, v221, 64, v77
	v_mov_b32_e32 v46, 0xc0
	v_add_u32_e32 v42, 0, v122
	v_lshl_or_b32 v121, v43, 2, v46
	v_add_u32_e32 v46, v42, v98
	s_waitcnt vmcnt(12)
	ds_write_b128 v28, v[8:11]
	v_add_u32_e32 v8, v78, v80
	s_waitcnt vmcnt(11)
	ds_write_b128 v8, v[12:15] offset:17408
	s_waitcnt vmcnt(10)
	ds_write_b128 v8, v[18:21] offset:37888
	s_waitcnt vmcnt(9)
	ds_write_b128 v81, v[22:25] offset:48128
	v_add_co_u32_e32 v18, vcc, s44, v26
	s_nop 1
	v_addc_co_u32_e32 v19, vcc, 0, v27, vcc
	v_add_co_u32_e32 v22, vcc, s19, v26
	v_or_b32_e32 v26, s27, v79
	s_nop 0
	v_addc_co_u32_e32 v23, vcc, 0, v27, vcc
	v_lshlrev_b32_e32 v120, 1, v26
	global_load_dwordx4 v[8:11], v[18:19], off offset:1536
	global_load_dwordx4 v[12:15], v[18:19], off offset:2560
	s_nop 0
	global_load_dwordx4 v[18:21], v[18:19], off offset:3584
	v_add_u32_e32 v28, v97, v120
	global_load_dwordx4 v[22:25], v[22:23], off offset:512
	v_lshl_or_b32 v222, s27, 1, v104
	v_mul_u32_u24_e32 v236, 0x140, v95
	v_add_u32_e32 v236, v236, v222
	s_waitcnt lgkmcnt(0)
	s_barrier
	s_mov_b32 s28, 0
	v_add3_u32 v68, s28, v96, v120
	ds_read_b64_tr_b16 v[66:67], v68 offset:17408
	ds_read_b64_tr_b16 v[68:69], v68 offset:18688
	v_add_u32_e32 v138, s28, v236
	v_add3_u32 v139, s28, v109, v222
	ds_read_b64 v[180:181], v138 offset:17408
	ds_read_b64 v[182:183], v138 offset:22528
	ds_read_b64 v[184:185], v139
	ds_read_b64 v[186:187], v139 offset:4352
	s_waitcnt lgkmcnt(4)
	v_mfma_f32_16x16x32_bf16 v[70:73], v[66:69], v[4:7], 0
	v_mfma_f32_16x16x32_bf16 v[66:69], v[66:69], v[0:3], 0
	s_mov_b32 s23, 0x42e60000
	s_waitcnt lgkmcnt(0)
	v_lshlrev_b32_e32 v188, 16, v180
	v_and_b32_e32 v189, 0xffff0000, v180
	v_lshlrev_b32_e32 v190, 16, v181
	v_and_b32_e32 v191, 0xffff0000, v181
	v_lshlrev_b32_e32 v192, 16, v182
	v_and_b32_e32 v193, 0xffff0000, v182
	v_lshlrev_b32_e32 v194, 16, v183
	v_and_b32_e32 v195, 0xffff0000, v183
	v_lshlrev_b32_e32 v196, 16, v184
	v_and_b32_e32 v197, 0xffff0000, v184
	v_lshlrev_b32_e32 v198, 16, v185
	v_and_b32_e32 v199, 0xffff0000, v185
	v_lshlrev_b32_e32 v200, 16, v186
	v_and_b32_e32 v201, 0xffff0000, v186
	v_lshlrev_b32_e32 v202, 16, v187
	v_and_b32_e32 v203, 0xffff0000, v187
	v_exp_f32_e32 v188, v188
	v_exp_f32_e32 v189, v189
	v_exp_f32_e32 v190, v190
	v_exp_f32_e32 v191, v191
	v_exp_f32_e32 v192, v192
	v_exp_f32_e32 v193, v193
	v_exp_f32_e32 v194, v194
	v_exp_f32_e32 v195, v195
	v_sub_f32_e32 v188, 1.0, v188
	v_sub_f32_e32 v189, 1.0, v189
	v_sub_f32_e32 v190, 1.0, v190
	v_sub_f32_e32 v191, 1.0, v191
	v_sub_f32_e32 v192, 1.0, v192
	v_sub_f32_e32 v193, 1.0, v193
	v_sub_f32_e32 v194, 1.0, v194
	v_sub_f32_e32 v195, 1.0, v195
	v_exp_f32_e32 v204, v70
	v_exp_f32_e32 v205, v71
	v_exp_f32_e32 v206, v72
	v_exp_f32_e32 v207, v73
	v_exp_f32_e32 v208, v66
	v_exp_f32_e32 v209, v67
	v_exp_f32_e32 v210, v68
	v_exp_f32_e32 v211, v69
	v_sub_f32_dpp v126, v66, v70 row_newbcast:15 row_mask:0xf bank_mask:0xf
	v_sub_f32_dpp v127, v67, v71 row_newbcast:15 row_mask:0xf bank_mask:0xf
	v_sub_f32_dpp v128, v68, v72 row_newbcast:15 row_mask:0xf bank_mask:0xf
	v_sub_f32_dpp v129, v69, v73 row_newbcast:15 row_mask:0xf bank_mask:0xf
	v_sub_f32_dpp v130, v66, v66 row_newbcast:15 row_mask:0xf bank_mask:0xf
	v_sub_f32_dpp v131, v67, v67 row_newbcast:15 row_mask:0xf bank_mask:0xf
	v_sub_f32_dpp v132, v68, v68 row_newbcast:15 row_mask:0xf bank_mask:0xf
	v_sub_f32_dpp v133, v69, v69 row_newbcast:15 row_mask:0xf bank_mask:0xf
	v_mul_f32_e32 v196, v196, v204
	v_mul_f32_e32 v197, v197, v205
	v_mul_f32_e32 v198, v198, v206
	v_mul_f32_e32 v199, v199, v207
	v_mul_f32_e32 v200, v200, v208
	v_mul_f32_e32 v201, v201, v209
	v_mul_f32_e32 v202, v202, v210
	v_mul_f32_e32 v203, v203, v211
	v_min_f32_e64 v204, -v70, s23
	v_min_f32_e64 v205, -v71, s23
	v_min_f32_e64 v206, -v72, s23
	v_min_f32_e64 v207, -v73, s23
	v_min_f32_e64 v208, -v66, s23
	v_min_f32_e64 v209, -v67, s23
	v_min_f32_e64 v210, -v68, s23
	v_min_f32_e64 v211, -v69, s23
	v_exp_f32_e32 v126, v126
	v_exp_f32_e32 v127, v127
	v_exp_f32_e32 v128, v128
	v_exp_f32_e32 v129, v129
	v_exp_f32_e32 v130, v130
	v_exp_f32_e32 v131, v131
	v_exp_f32_e32 v132, v132
	v_exp_f32_e32 v133, v133
	v_exp_f32_e32 v204, v204
	v_exp_f32_e32 v205, v205
	v_exp_f32_e32 v206, v206
	v_exp_f32_e32 v207, v207
	v_exp_f32_e32 v208, v208
	v_exp_f32_e32 v209, v209
	v_exp_f32_e32 v210, v210
	v_exp_f32_e32 v211, v211
	v_exp_f32_e32 v212, v66
	v_exp_f32_e32 v213, v67
	v_exp_f32_e32 v214, v68
	v_exp_f32_e32 v215, v69
	v_mul_f32_e32 v126, v126, v188
	v_mul_f32_e32 v127, v127, v189
	v_mul_f32_e32 v128, v128, v190
	v_mul_f32_e32 v129, v129, v191
	v_mul_f32_e32 v130, v130, v192
	v_mul_f32_e32 v131, v131, v193
	v_mul_f32_e32 v132, v132, v194
	v_mul_f32_e32 v133, v133, v195
	v_mul_f32_e32 v204, v204, v188
	v_mul_f32_e32 v205, v205, v189
	v_mul_f32_e32 v206, v206, v190
	v_mul_f32_e32 v207, v207, v191
	v_mul_f32_e32 v208, v208, v192
	v_mul_f32_e32 v209, v209, v193
	v_mul_f32_e32 v210, v210, v194
	v_mul_f32_e32 v211, v211, v195
	v_lshl_add_u32 v216, v222, 1, s28
	v_cvt_pk_bf16_f32 v180, v196, v197
	v_cvt_pk_bf16_f32 v181, v198, v199
	v_cvt_pk_bf16_f32 v182, v200, v201
	v_cvt_pk_bf16_f32 v183, v202, v203
	v_cvt_pk_bf16_f32 v184, v204, v205
	v_cvt_pk_bf16_f32 v185, v206, v207
	v_cvt_pk_bf16_f32 v186, v208, v209
	v_cvt_pk_bf16_f32 v187, v210, v211
	v_cvt_pk_bf16_f32 v134, v126, v127
	v_cvt_pk_bf16_f32 v135, v128, v129
	v_cvt_pk_bf16_f32 v136, v130, v131
	v_cvt_pk_bf16_f32 v137, v132, v133
	ds_write_b64 v139, v[180:181]
	ds_write_b64 v139, v[182:183] offset:4352
	ds_write_b64 v139, v[184:185] offset:8704
	ds_write_b64 v139, v[186:187] offset:13056
	ds_write_b64 v138, v[134:135] offset:27648
	ds_write_b64 v138, v[136:137] offset:32768
	s_and_saveexec_b64 s[22:23], s[2:3]
	ds_write_b128 v216, v[212:215] offset:56832
